# v83 with the early L2 writeback issued by the 16th-from-last arriver (was 8th)
# baseline (speedup 1.0000x reference)
.LBB0_182:
	s_or_b64 exec, exec, s[12:13]
	v_cvt_f32_u32_e32 v4, v2
	s_waitcnt vmcnt(0)
	v_readfirstlane_b32 s10, v3
	v_sub_u32_e32 v3, 0, v2
	v_rcp_iflag_f32_e32 v4, v4
	v_add_u32_e32 v5, s10, v1
	v_mul_f32_e32 v4, 0x4f7ffffe, v4
	v_cvt_u32_f32_e32 v4, v4
	v_mul_lo_u32 v1, v3, v4
	v_mul_hi_u32 v1, v4, v1
	v_add_u32_e32 v1, v4, v1
	v_mul_hi_u32 v1, v5, v1
	v_mul_lo_u32 v3, v1, v2
	v_sub_u32_e32 v3, v5, v3
	v_add_u32_e32 v4, 1, v1
	v_cmp_ge_u32_e32 vcc, v3, v2
	s_nop 1
	v_cndmask_b32_e32 v1, v1, v4, vcc
	v_sub_u32_e32 v4, v3, v2
	v_cndmask_b32_e32 v3, v3, v4, vcc
	v_add_u32_e32 v4, 1, v1
	v_cmp_ge_u32_e32 vcc, v3, v2
	v_add_u32_e32 v3, 1, v5
	s_nop 0
	v_cndmask_b32_e32 v1, v1, v4, vcc
	v_mul_lo_u32 v4, v2, v1
	v_add_u32_e32 v2, v4, v2
	v_cmp_ne_u32_e32 vcc, v3, v2
	s_and_saveexec_b64 s[10:11], vcc
	s_xor_b64 s[10:11], exec, s[10:11]
	s_cbranch_execz .LBB0_196
	v_add_u32_e32 v0, 16, v5
	v_cmp_eq_u32_e32 vcc, v0, v2
	s_and_b64 vcc, exec, vcc
	s_cbranch_vccz .Lfirstwb_skip_0
	buffer_wbl2 sc1

.LBB0_1296:
	s_or_b64 exec, exec, s[16:17]
	v_cvt_f32_u32_e32 v4, v2
	s_waitcnt vmcnt(0)
	v_readfirstlane_b32 s12, v3
	v_sub_u32_e32 v3, 0, v2
	v_rcp_iflag_f32_e32 v4, v4
	v_add_u32_e32 v5, s12, v1
	v_mul_f32_e32 v4, 0x4f7ffffe, v4
	v_cvt_u32_f32_e32 v4, v4
	v_mul_lo_u32 v1, v3, v4
	v_mul_hi_u32 v1, v4, v1
	v_add_u32_e32 v1, v4, v1
	v_mul_hi_u32 v1, v5, v1
	v_mul_lo_u32 v3, v1, v2
	v_sub_u32_e32 v3, v5, v3
	v_add_u32_e32 v4, 1, v1
	v_cmp_ge_u32_e32 vcc, v3, v2
	s_nop 1
	v_cndmask_b32_e32 v1, v1, v4, vcc
	v_sub_u32_e32 v4, v3, v2
	v_cndmask_b32_e32 v3, v3, v4, vcc
	v_add_u32_e32 v4, 1, v1
	v_cmp_ge_u32_e32 vcc, v3, v2
	v_add_u32_e32 v3, 1, v5
	s_nop 0
	v_cndmask_b32_e32 v1, v1, v4, vcc
	v_mul_lo_u32 v4, v2, v1
	v_add_u32_e32 v2, v4, v2
	v_cmp_ne_u32_e32 vcc, v3, v2
	s_and_saveexec_b64 s[12:13], vcc
	s_xor_b64 s[12:13], exec, s[12:13]
	s_cbranch_execz .LBB0_1310
	v_add_u32_e32 v0, 16, v5
	v_cmp_eq_u32_e32 vcc, v0, v2
	s_and_b64 vcc, exec, vcc
	s_cbranch_vccz .Lfirstwb_skip_3
	buffer_wbl2 sc1

.LBB0_1953:
	s_or_b64 exec, exec, s[14:15]
	v_cvt_f32_u32_e32 v4, v2
	s_waitcnt vmcnt(0)
	v_readfirstlane_b32 s12, v3
	v_sub_u32_e32 v3, 0, v2
	v_rcp_iflag_f32_e32 v4, v4
	v_add_u32_e32 v5, s12, v1
	v_mul_f32_e32 v4, 0x4f7ffffe, v4
	v_cvt_u32_f32_e32 v4, v4
	v_mul_lo_u32 v1, v3, v4
	v_mul_hi_u32 v1, v4, v1
	v_add_u32_e32 v1, v4, v1
	v_mul_hi_u32 v1, v5, v1
	v_mul_lo_u32 v3, v1, v2
	v_sub_u32_e32 v3, v5, v3
	v_add_u32_e32 v4, 1, v1
	v_cmp_ge_u32_e32 vcc, v3, v2
	s_nop 1
	v_cndmask_b32_e32 v1, v1, v4, vcc
	v_sub_u32_e32 v4, v3, v2
	v_cndmask_b32_e32 v3, v3, v4, vcc
	v_add_u32_e32 v4, 1, v1
	v_cmp_ge_u32_e32 vcc, v3, v2
	v_add_u32_e32 v3, 1, v5
	s_nop 0
	v_cndmask_b32_e32 v1, v1, v4, vcc
	v_mul_lo_u32 v4, v2, v1
	v_add_u32_e32 v2, v4, v2
	v_cmp_ne_u32_e32 vcc, v3, v2
	s_and_saveexec_b64 s[12:13], vcc
	s_xor_b64 s[12:13], exec, s[12:13]
	s_cbranch_execz .LBB0_1967
	v_add_u32_e32 v0, 16, v5
	v_cmp_eq_u32_e32 vcc, v0, v2
	s_and_b64 vcc, exec, vcc
	s_cbranch_vccz .Lfirstwb_skip_4
	buffer_wbl2 sc1
